# P10 residual phase: all 32 row data loads issued together (renamed X-load destinations), on hoist3
# speedup vs baseline: 1.0008x; 1.0008x over previous
.LBB0_912:
	s_and_b32 s0, s18, 0x8000
	s_and_b32 s1, s7, 0xfffff000
	s_add_i32 s0, s0, s1
	s_and_b32 s1, s4, 0xffc
	s_or_b32 s0, s0, s1
	s_ashr_i32 s1, s0, 31
	s_lshl_b64 s[0:1], s[0:1], 11
	s_ashr_i32 s5, s4, 31
	v_lshl_add_u64 v[64:65], v[4:5], 0, s[0:1]
	s_lshl_b64 s[10:11], s[4:5], 11
	v_lshl_add_u64 v[0:1], v[6:7], 0, s[10:11]
	global_load_dwordx2 v[80:81], v[64:65], off
	global_load_dwordx2 v[2:3], v[0:1], off
	s_add_i32 s0, s4, 1
	s_ashr_i32 s1, s0, 31
	s_lshl_b64 s[0:1], s[0:1], 11
	v_lshl_add_u64 v[40:41], v[6:7], 0, s[0:1]
	s_add_i32 s0, s4, 2
	s_ashr_i32 s1, s0, 31
	s_lshl_b64 s[0:1], s[0:1], 11
	v_lshl_add_u64 v[88:89], v[6:7], 0, s[0:1]
	s_movk_i32 s0, 0x1000
	v_add_co_u32_e32 v90, vcc, s0, v64
	s_add_i32 s0, s4, 3
	s_nop 0
	v_addc_co_u32_e32 v91, vcc, 0, v65, vcc
	s_ashr_i32 s1, s0, 31
	s_lshl_b64 s[0:1], s[0:1], 11
	v_lshl_add_u64 v[106:107], v[6:7], 0, s[0:1]
	s_mov_b32 s17, s11
	global_load_dwordx2 v[82:83], v[64:65], off offset:512
	global_load_dwordx2 v[202:203], v[0:1], off offset:512
	global_load_dwordx2 v[84:85], v[64:65], off offset:1024
	global_load_dwordx2 v[204:205], v[0:1], off offset:1024
	global_load_dwordx2 v[86:87], v[64:65], off offset:1536
	global_load_dwordx2 v[32:33], v[0:1], off offset:1536
	global_load_dwordx2 v[96:97], v[64:65], off offset:2048
	global_load_dwordx2 v[44:45], v[40:41], off
	global_load_dwordx2 v[126:127], v[64:65], off offset:2560
	global_load_dwordx2 v[206:207], v[40:41], off offset:512
	global_load_dwordx2 v[128:129], v[64:65], off offset:3072
	global_load_dwordx2 v[220:221], v[40:41], off offset:1024
	global_load_dwordx2 v[140:141], v[64:65], off offset:3584
	global_load_dwordx2 v[46:47], v[40:41], off offset:1536
	global_load_dwordx2 v[98:99], v[90:91], off
	global_load_dwordx2 v[64:65], v[88:89], off
	global_load_dwordx2 v[100:101], v[90:91], off offset:512
	global_load_dwordx2 v[222:223], v[88:89], off offset:512
	global_load_dwordx2 v[142:143], v[90:91], off offset:1024
	global_load_dwordx2 v[224:225], v[88:89], off offset:1024
	global_load_dwordx2 v[148:149], v[90:91], off offset:1536
	global_load_dwordx2 v[76:77], v[88:89], off offset:1536
	global_load_dwordx2 v[150:151], v[90:91], off offset:2048
	global_load_dwordx2 v[78:79], v[106:107], off
	global_load_dwordx2 v[152:153], v[90:91], off offset:2560
	global_load_dwordx2 v[92:93], v[106:107], off offset:512
	global_load_dwordx2 v[160:161], v[90:91], off offset:3072
	global_load_dwordx2 v[226:227], v[106:107], off offset:1024
	global_load_dwordx2 v[174:175], v[90:91], off offset:3584
	global_load_dwordx2 v[90:91], v[106:107], off offset:1536
	s_waitcnt vmcnt(0)
	v_lshlrev_b32_e32 v48, 16, v2
	v_and_b32_e32 v49, 0xffff0000, v2
	v_lshlrev_b32_e32 v50, 16, v3
	v_and_b32_e32 v51, 0xffff0000, v3
	v_lshlrev_b32_e32 v38, 16, v202
	v_and_b32_e32 v39, 0xffff0000, v202
	v_lshlrev_b32_e32 v42, 16, v203
	v_and_b32_e32 v43, 0xffff0000, v203
	v_lshlrev_b32_e32 v132, 16, v84
	v_and_b32_e32 v133, 0xffff0000, v84
	v_lshlrev_b32_e32 v134, 16, v85
	v_lshlrev_b32_e32 v60, 16, v44
	v_and_b32_e32 v61, 0xffff0000, v44
	v_lshlrev_b32_e32 v62, 16, v45
	v_and_b32_e32 v63, 0xffff0000, v45
	v_and_b32_e32 v135, 0xffff0000, v85
	v_lshlrev_b32_e32 v121, 16, v86
	v_and_b32_e32 v119, 0xffff0000, v86
	v_mul_f32_e32 v118, v119, v119
	v_lshlrev_b32_e32 v34, 16, v204
	v_and_b32_e32 v35, 0xffff0000, v204
	v_lshlrev_b32_e32 v36, 16, v205
	v_and_b32_e32 v37, 0xffff0000, v205
	v_lshlrev_b32_e32 v2, 16, v32
	v_and_b32_e32 v3, 0xffff0000, v32
	v_lshlrev_b32_e32 v32, 16, v33
	v_and_b32_e32 v33, 0xffff0000, v33
	v_lshlrev_b32_e32 v56, 16, v206
	v_and_b32_e32 v57, 0xffff0000, v206
	v_lshlrev_b32_e32 v58, 16, v207
	v_and_b32_e32 v59, 0xffff0000, v207
	s_nop 0
	v_lshlrev_b32_e32 v138, 16, v129
	v_and_b32_e32 v139, 0xffff0000, v129
	v_and_b32_e32 v129, 0xffff0000, v140
	v_lshlrev_b32_e32 v72, 16, v64
	v_and_b32_e32 v73, 0xffff0000, v64
	v_lshlrev_b32_e32 v74, 16, v65
	v_and_b32_e32 v75, 0xffff0000, v65
	v_lshlrev_b32_e32 v176, 16, v98
	v_and_b32_e32 v177, 0xffff0000, v98
	v_lshlrev_b32_e32 v98, 16, v99
	v_and_b32_e32 v99, 0xffff0000, v99
	v_lshlrev_b32_e32 v52, 16, v220
	v_and_b32_e32 v53, 0xffff0000, v220
	v_lshlrev_b32_e32 v54, 16, v221
	v_and_b32_e32 v55, 0xffff0000, v221
	v_lshlrev_b32_e32 v44, 16, v46
	v_and_b32_e32 v45, 0xffff0000, v46
	v_lshlrev_b32_e32 v46, 16, v47
	v_and_b32_e32 v47, 0xffff0000, v47
	v_and_b32_e32 v165, 0xffff0000, v101
	v_lshlrev_b32_e32 v66, 16, v222
	v_and_b32_e32 v67, 0xffff0000, v222
	v_lshlrev_b32_e32 v68, 16, v223
	v_and_b32_e32 v69, 0xffff0000, v223
	v_and_b32_e32 v164, 0xffff0000, v100
	v_lshlrev_b32_e32 v163, 16, v101
	v_lshlrev_b32_e32 v162, 16, v100
	v_pk_mul_f32 v[100:101], v[164:165], v[164:165]
	v_lshlrev_b32_e32 v70, 16, v224
	v_pk_fma_f32 v[100:101], v[162:163], v[162:163], v[100:101]
	v_and_b32_e32 v181, 0xffff0000, v151
	v_lshlrev_b32_e32 v122, 16, v92
	v_and_b32_e32 v123, 0xffff0000, v92
	v_lshlrev_b32_e32 v124, 16, v93
	v_and_b32_e32 v125, 0xffff0000, v93
	s_nop 0
	v_pk_add_f32 v[100:101], v[100:101], v[100:101] op_sel:[0,1] op_sel_hi:[1,0]
	v_and_b32_e32 v179, 0xffff0000, v150
	v_lshlrev_b32_e32 v180, 16, v151
	v_and_b32_e32 v173, 0xffff0000, v153
	v_lshlrev_b32_e32 v178, 16, v150
	v_lshlrev_b32_e32 v102, 16, v76
	v_and_b32_e32 v103, 0xffff0000, v76
	v_lshlrev_b32_e32 v104, 16, v77
	v_and_b32_e32 v105, 0xffff0000, v77
	v_lshlrev_b32_e32 v76, 16, v78
	v_and_b32_e32 v77, 0xffff0000, v78
	v_lshlrev_b32_e32 v78, 16, v79
	v_and_b32_e32 v79, 0xffff0000, v79
	v_and_b32_e32 v71, 0xffff0000, v224
	v_lshlrev_b32_e32 v64, 16, v225
	v_and_b32_e32 v65, 0xffff0000, v225
	v_and_b32_e32 v151, 0xffff0000, v174
	v_lshlrev_b32_e32 v114, 16, v227
	v_and_b32_e32 v115, 0xffff0000, v227
	v_and_b32_e32 v93, 0xffff0000, v81
	v_lshlrev_b32_e32 v112, 16, v226
	v_and_b32_e32 v113, 0xffff0000, v226
	v_lshlrev_b32_e32 v108, 16, v90
	v_and_b32_e32 v109, 0xffff0000, v90
	v_lshlrev_b32_e32 v110, 16, v91
	v_and_b32_e32 v111, 0xffff0000, v91
	v_lshlrev_b32_e32 v90, 16, v80
	v_and_b32_e32 v91, 0xffff0000, v80
	v_lshlrev_b32_e32 v92, 16, v81
	v_mul_f32_e32 v80, v93, v93
	v_pk_fma_f32 v[94:95], v[92:93], v[92:93], v[80:81] op_sel_hi:[1,1,0]
	v_lshlrev_b32_e32 v81, 16, v83
	v_lshlrev_b32_e32 v80, 16, v82
	v_and_b32_e32 v83, 0xffff0000, v83
	v_and_b32_e32 v82, 0xffff0000, v82
	v_mul_f32_e32 v84, v91, v91
	v_pk_mul_f32 v[116:117], v[82:83], v[82:83]
	v_pk_fma_f32 v[84:85], v[90:91], v[90:91], v[84:85] op_sel_hi:[1,1,0]
	v_pk_fma_f32 v[130:131], v[80:81], v[80:81], v[116:117]
	v_lshlrev_b32_e32 v116, 16, v87
	v_and_b32_e32 v117, 0xffff0000, v87
	v_mov_b32_e32 v120, v84
	v_mov_b32_e32 v86, v94
	v_mov_b32_e32 v87, v121
	v_pk_add_f32 v[84:85], v[84:85], v[94:95]
	v_pk_mul_f32 v[86:87], v[120:121], v[86:87]
	v_mul_f32_e32 v94, v135, v135
	v_mov_b32_e32 v85, v87
	v_pk_add_f32 v[86:87], v[130:131], v[130:131] op_sel:[0,1] op_sel_hi:[1,0]
	v_mul_f32_e32 v136, v116, v116
	v_mov_b32_e32 v87, v118
	v_pk_add_f32 v[84:85], v[84:85], v[86:87]
	v_mul_f32_e32 v86, v133, v133
	v_mul_f32_e32 v137, v117, v117
	v_pk_fma_f32 v[86:87], v[132:133], v[132:133], v[86:87] op_sel_hi:[1,1,0]
	v_pk_fma_f32 v[94:95], v[134:135], v[134:135], v[94:95] op_sel_hi:[1,1,0]
	v_mov_b32_e32 v87, v136
	v_mov_b32_e32 v95, v137
	v_pk_add_f32 v[86:87], v[86:87], v[94:95]
	v_lshlrev_b32_e32 v94, 16, v96
	v_and_b32_e32 v95, 0xffff0000, v96
	v_lshlrev_b32_e32 v96, 16, v97
	v_and_b32_e32 v97, 0xffff0000, v97
	v_pk_add_f32 v[144:145], v[84:85], v[86:87]
	v_mul_f32_e32 v84, v97, v97
	v_and_b32_e32 v87, 0xffff0000, v127
	v_and_b32_e32 v86, 0xffff0000, v126
	v_pk_fma_f32 v[146:147], v[96:97], v[96:97], v[84:85] op_sel_hi:[1,1,0]
	v_lshlrev_b32_e32 v85, 16, v127
	v_lshlrev_b32_e32 v84, 16, v126
	v_pk_mul_f32 v[126:127], v[86:87], v[86:87]
	v_mul_f32_e32 v118, v95, v95
	v_pk_fma_f32 v[154:155], v[84:85], v[84:85], v[126:127]
	v_lshlrev_b32_e32 v131, 16, v140
	v_lshlrev_b32_e32 v126, 16, v141
	v_and_b32_e32 v127, 0xffff0000, v141
	v_pk_fma_f32 v[140:141], v[94:95], v[94:95], v[118:119] op_sel_hi:[1,1,0]
	v_mov_b32_e32 v156, v146
	v_mov_b32_e32 v130, v140
	v_mov_b32_e32 v157, v131
	v_pk_add_f32 v[140:141], v[140:141], v[146:147]
	v_pk_mul_f32 v[146:147], v[130:131], v[156:157]
	v_and_b32_e32 v137, 0xffff0000, v128
	v_mul_f32_e32 v120, v129, v129
	v_mov_b32_e32 v141, v147
	v_pk_add_f32 v[146:147], v[154:155], v[154:155] op_sel:[0,1] op_sel_hi:[1,0]
	v_lshlrev_b32_e32 v136, 16, v128
	v_mov_b32_e32 v147, v120
	v_mul_f32_e32 v118, v137, v137
	v_pk_add_f32 v[140:141], v[140:141], v[146:147]
	v_pk_fma_f32 v[146:147], v[136:137], v[136:137], v[118:119] op_sel_hi:[1,1,0]
	v_mul_f32_e32 v118, v139, v139
	v_mul_f32_e32 v128, v126, v126
	v_mul_f32_e32 v158, v127, v127
	v_pk_fma_f32 v[154:155], v[138:139], v[138:139], v[118:119] op_sel_hi:[1,1,0]
	v_mov_b32_e32 v147, v128
	v_mov_b32_e32 v155, v158
	v_pk_add_f32 v[146:147], v[146:147], v[154:155]
	v_lshlrev_b32_e32 v154, 16, v142
	v_pk_add_f32 v[140:141], v[140:141], v[146:147]
	v_mov_b32_e32 v147, v144
	v_mov_b32_e32 v146, v140
	v_mov_b32_e32 v144, v141
	v_pk_add_f32 v[140:141], v[146:147], v[144:145]
	ds_bpermute_b32 v145, v184, v141
	ds_bpermute_b32 v144, v184, v140
	v_and_b32_e32 v155, 0xffff0000, v142
	v_lshlrev_b32_e32 v156, 16, v143
	v_and_b32_e32 v157, 0xffff0000, v143
	v_lshlrev_b32_e32 v147, 16, v148
	s_waitcnt lgkmcnt(0)
	v_pk_add_f32 v[140:141], v[140:141], v[144:145]
	ds_bpermute_b32 v145, v185, v141
	ds_bpermute_b32 v144, v185, v140
	v_lshlrev_b32_e32 v142, 16, v149
	v_and_b32_e32 v143, 0xffff0000, v149
	v_mov_b32_e32 v167, v147
	v_mul_f32_e32 v172, v143, v143
	s_waitcnt lgkmcnt(0)
	v_pk_add_f32 v[140:141], v[140:141], v[144:145]
	ds_bpermute_b32 v145, v186, v141
	ds_bpermute_b32 v144, v186, v140
	s_waitcnt lgkmcnt(0)
	v_pk_add_f32 v[140:141], v[140:141], v[144:145]
	ds_bpermute_b32 v145, v187, v141
	ds_bpermute_b32 v144, v187, v140
	s_waitcnt lgkmcnt(0)
	v_pk_add_f32 v[140:141], v[140:141], v[144:145]
	ds_bpermute_b32 v145, v188, v141
	ds_bpermute_b32 v144, v188, v140
	s_waitcnt lgkmcnt(0)
	v_pk_add_f32 v[140:141], v[140:141], v[144:145]
	ds_bpermute_b32 v145, v189, v141
	ds_bpermute_b32 v144, v189, v140
	s_waitcnt lgkmcnt(0)
	v_pk_add_f32 v[144:145], v[140:141], v[144:145]
	v_mov_b64_e32 v[140:141], s[8:9]
	v_pk_fma_f32 v[144:145], v[144:145], s[6:7], v[140:141] op_sel_hi:[1,0,0]
	s_nop 0
	v_mul_f32_e32 v118, 0x4b800000, v145
	v_cmp_gt_f32_e64 s[0:1], s21, v145
	v_cmp_gt_f32_e32 vcc, s21, v144
	s_nop 0
	v_cndmask_b32_e64 v118, v145, v118, s[0:1]
	v_rsq_f32_e32 v118, v118
	v_and_b32_e32 v145, 0xffff0000, v148
	v_mul_f32_e32 v130, v145, v145
	v_mov_b32_e32 v101, v130
	v_mul_f32_e32 v120, 0x45800000, v118
	v_cndmask_b32_e64 v128, v118, v120, s[0:1]
	v_mul_f32_e32 v118, 0x4b800000, v144
	v_cndmask_b32_e32 v118, v144, v118, vcc
	v_rsq_f32_e32 v118, v118
	v_mul_f32_e32 v144, v142, v142
	v_mul_f32_e32 v130, v151, v151
	v_pk_mul_f32 v[90:91], v[128:129], v[90:91] op_sel_hi:[0,1]
	v_mul_f32_e32 v120, 0x45800000, v118
	v_cndmask_b32_e32 v120, v118, v120, vcc
	v_mul_f32_e32 v118, v99, v99
	v_pk_fma_f32 v[158:159], v[98:99], v[98:99], v[118:119] op_sel_hi:[1,1,0]
	v_mul_f32_e32 v118, v177, v177
	v_pk_fma_f32 v[148:149], v[176:177], v[176:177], v[118:119] op_sel_hi:[1,1,0]
	v_mov_b32_e32 v166, v158
	v_mov_b32_e32 v146, v148
	v_pk_add_f32 v[148:149], v[148:149], v[158:159]
	v_pk_mul_f32 v[158:159], v[146:147], v[166:167]
	v_mul_f32_e32 v118, v155, v155
	v_mov_b32_e32 v149, v159
	v_pk_add_f32 v[100:101], v[148:149], v[100:101]
	v_pk_fma_f32 v[148:149], v[154:155], v[154:155], v[118:119] op_sel_hi:[1,1,0]
	v_mul_f32_e32 v118, v157, v157
	v_pk_fma_f32 v[158:159], v[156:157], v[156:157], v[118:119] op_sel_hi:[1,1,0]
	v_mov_b32_e32 v149, v144
	v_mov_b32_e32 v159, v172
	v_pk_add_f32 v[148:149], v[148:149], v[158:159]
	v_mul_f32_e32 v118, v181, v181
	v_and_b32_e32 v172, 0xffff0000, v152
	v_pk_add_f32 v[100:101], v[100:101], v[148:149]
	v_pk_fma_f32 v[182:183], v[180:181], v[180:181], v[118:119] op_sel_hi:[1,1,0]
	v_lshlrev_b32_e32 v167, 16, v153
	v_lshlrev_b32_e32 v166, 16, v152
	v_pk_mul_f32 v[148:149], v[172:173], v[172:173]
	v_mul_f32_e32 v118, v179, v179
	v_pk_fma_f32 v[194:195], v[166:167], v[166:167], v[148:149]
	v_lshlrev_b32_e32 v153, 16, v174
	v_lshlrev_b32_e32 v148, 16, v175
	v_and_b32_e32 v149, 0xffff0000, v175
	v_pk_fma_f32 v[174:175], v[178:179], v[178:179], v[118:119] op_sel_hi:[1,1,0]
	v_mov_b32_e32 v196, v182
	v_mov_b32_e32 v152, v174
	v_mov_b32_e32 v197, v153
	v_pk_add_f32 v[174:175], v[174:175], v[182:183]
	v_pk_mul_f32 v[182:183], v[152:153], v[196:197]
	v_and_b32_e32 v159, 0xffff0000, v160
	v_mov_b32_e32 v175, v183
	v_pk_add_f32 v[182:183], v[194:195], v[194:195] op_sel:[0,1] op_sel_hi:[1,0]
	v_lshlrev_b32_e32 v158, 16, v160
	v_lshlrev_b32_e32 v160, 16, v161
	v_and_b32_e32 v161, 0xffff0000, v161
	v_mov_b32_e32 v183, v130
	v_mul_f32_e32 v118, v159, v159
	v_pk_add_f32 v[174:175], v[174:175], v[182:183]
	v_pk_fma_f32 v[182:183], v[158:159], v[158:159], v[118:119] op_sel_hi:[1,1,0]
	v_mul_f32_e32 v118, v161, v161
	v_mul_f32_e32 v144, v148, v148
	v_mul_f32_e32 v146, v149, v149
	v_pk_fma_f32 v[194:195], v[160:161], v[160:161], v[118:119] op_sel_hi:[1,1,0]
	v_mov_b32_e32 v183, v144
	v_mov_b32_e32 v195, v146
	v_pk_add_f32 v[182:183], v[182:183], v[194:195]
	v_pk_mul_f32 v[92:93], v[128:129], v[92:93] op_sel_hi:[0,1]
	v_pk_add_f32 v[174:175], v[174:175], v[182:183]
	v_mov_b32_e32 v183, v100
	v_mov_b32_e32 v182, v174
	v_mov_b32_e32 v100, v175
	v_pk_add_f32 v[100:101], v[182:183], v[100:101]
	ds_bpermute_b32 v175, v184, v101
	ds_bpermute_b32 v174, v184, v100
	v_mov_b32_e32 v144, v147
	v_mov_b32_e32 v150, v153
	s_waitcnt lgkmcnt(0)
	v_pk_add_f32 v[100:101], v[100:101], v[174:175]
	ds_bpermute_b32 v175, v185, v101
	ds_bpermute_b32 v174, v185, v100
	s_waitcnt lgkmcnt(0)
	v_pk_add_f32 v[100:101], v[100:101], v[174:175]
	ds_bpermute_b32 v175, v186, v101
	ds_bpermute_b32 v174, v186, v100
	s_waitcnt lgkmcnt(0)
	v_pk_add_f32 v[100:101], v[100:101], v[174:175]
	ds_bpermute_b32 v175, v187, v101
	ds_bpermute_b32 v174, v187, v100
	s_waitcnt lgkmcnt(0)
	v_pk_add_f32 v[100:101], v[100:101], v[174:175]
	ds_bpermute_b32 v175, v188, v101
	ds_bpermute_b32 v174, v188, v100
	s_waitcnt lgkmcnt(0)
	v_pk_add_f32 v[100:101], v[100:101], v[174:175]
	ds_bpermute_b32 v175, v189, v101
	ds_bpermute_b32 v174, v189, v100
	s_waitcnt lgkmcnt(0)
	v_pk_add_f32 v[100:101], v[100:101], v[174:175]
	s_nop 0
	v_pk_fma_f32 v[100:101], v[100:101], s[6:7], v[140:141] op_sel_hi:[1,0,0]
	s_nop 0
	v_mul_f32_e32 v118, 0x4b800000, v101
	v_cmp_gt_f32_e64 s[0:1], s21, v101
	v_cmp_gt_f32_e32 vcc, s21, v100
	s_nop 0
	v_cndmask_b32_e64 v101, v101, v118, s[0:1]
	v_rsq_f32_e32 v101, v101
	s_nop 0
	v_mul_f32_e32 v118, 0x45800000, v101
	v_cndmask_b32_e64 v146, v101, v118, s[0:1]
	s_ashr_i32 s0, s2, 11
	s_mul_i32 s0, s0, 9
	s_ashr_i32 s1, s0, 31
	s_lshl_b64 s[0:1], s[0:1], 12
	s_add_u32 s5, s14, s0
	s_addc_u32 s13, s15, s1
	s_add_u32 s0, s5, 0x5000
	s_addc_u32 s1, s13, 0
	global_load_dwordx4 v[194:197], v190, s[0:1]
	global_load_dwordx4 v[198:201], v[10:11], off
	v_mul_f32_e32 v101, 0x4b800000, v100
	v_cndmask_b32_e32 v100, v100, v101, vcc
	v_rsq_f32_e32 v100, v100
	v_mov_b32_e32 v118, v121
	v_mul_f32_e32 v101, 0x45800000, v100
	v_cndmask_b32_e32 v130, v100, v101, vcc
	s_waitcnt vmcnt(0)
	v_pk_mul_f32 v[196:197], v[196:197], v[200:201]
	v_pk_mul_f32 v[194:195], v[194:195], v[198:199]
	v_pk_fma_f32 v[174:175], v[92:93], v[196:197], v[50:51]
	v_pk_fma_f32 v[182:183], v[90:91], v[194:195], v[48:49]
	v_cvt_pk_bf16_f32 v49, v174, v175
	v_cvt_pk_bf16_f32 v48, v182, v183
	global_store_dwordx2 v[0:1], v[48:49], off
	v_pk_mul_f32 v[48:49], v[174:175], v[174:175]
	v_pk_mul_f32 v[50:51], v[182:183], v[182:183]
	s_nop 0
	v_pk_mov_b32 v[90:91], v[50:51], v[48:49] op_sel:[1,0]
	v_mov_b32_e32 v51, v49
	v_pk_add_f32 v[198:199], v[90:91], v[50:51]
	v_pk_mul_f32 v[48:49], v[120:121], v[94:95] op_sel_hi:[0,1]
	v_pk_mul_f32 v[50:51], v[120:121], v[96:97] op_sel_hi:[0,1]
	v_pk_fma_f32 v[94:95], v[50:51], v[196:197], v[62:63]
	v_pk_fma_f32 v[96:97], v[48:49], v[194:195], v[60:61]
	v_cvt_pk_bf16_f32 v49, v94, v95
	v_cvt_pk_bf16_f32 v48, v96, v97
	global_store_dwordx2 v[40:41], v[48:49], off
	v_pk_mul_f32 v[48:49], v[94:95], v[94:95]
	v_pk_mul_f32 v[50:51], v[96:97], v[96:97]
	s_nop 0
	v_pk_mov_b32 v[60:61], v[50:51], v[48:49] op_sel:[1,0]
	v_mov_b32_e32 v51, v49
	v_pk_add_f32 v[200:201], v[60:61], v[50:51]
	v_pk_mul_f32 v[48:49], v[146:147], v[176:177] op_sel_hi:[0,1]
	v_pk_mul_f32 v[50:51], v[146:147], v[98:99] op_sel_hi:[0,1]
	v_pk_fma_f32 v[98:99], v[196:197], v[50:51], v[74:75]
	v_pk_fma_f32 v[100:101], v[194:195], v[48:49], v[72:73]
	v_cvt_pk_bf16_f32 v49, v98, v99
	v_cvt_pk_bf16_f32 v48, v100, v101
	global_store_dwordx2 v[88:89], v[48:49], off
	v_pk_mul_f32 v[48:49], v[98:99], v[98:99]
	v_pk_mul_f32 v[50:51], v[100:101], v[100:101]
	s_nop 0
	v_pk_mov_b32 v[60:61], v[50:51], v[48:49] op_sel:[1,0]
	v_mov_b32_e32 v51, v49
	v_pk_add_f32 v[176:177], v[60:61], v[50:51]
	v_pk_mul_f32 v[48:49], v[130:131], v[178:179] op_sel_hi:[0,1]
	v_pk_mul_f32 v[50:51], v[130:131], v[180:181] op_sel_hi:[0,1]
	v_pk_fma_f32 v[90:91], v[196:197], v[50:51], v[78:79]
	v_pk_fma_f32 v[92:93], v[194:195], v[48:49], v[76:77]
	v_cvt_pk_bf16_f32 v49, v90, v91
	v_cvt_pk_bf16_f32 v48, v92, v93
	global_store_dwordx2 v[106:107], v[48:49], off
	v_pk_mul_f32 v[48:49], v[90:91], v[90:91]
	v_pk_mul_f32 v[50:51], v[92:93], v[92:93]
	s_nop 0
	v_pk_mov_b32 v[60:61], v[50:51], v[48:49] op_sel:[1,0]
	v_mov_b32_e32 v51, v49
	v_pk_add_f32 v[178:179], v[60:61], v[50:51]
	global_load_dwordx4 v[48:51], v191, s[0:1]
	global_load_dwordx4 v[60:63], v[12:13], off
	s_waitcnt vmcnt(0)
	v_pk_mul_f32 v[48:49], v[48:49], v[60:61]
	v_mov_b32_e32 v60, v80
	v_mov_b32_e32 v61, v82
	v_mov_b32_e32 v82, v81
	v_pk_mul_f32 v[50:51], v[50:51], v[62:63]
	v_pk_mul_f32 v[60:61], v[128:129], v[60:61] op_sel_hi:[0,1]
	v_pk_mul_f32 v[62:63], v[128:129], v[82:83] op_sel_hi:[0,1]
	v_pk_fma_f32 v[76:77], v[62:63], v[50:51], v[42:43]
	v_pk_fma_f32 v[78:79], v[60:61], v[48:49], v[38:39]
	v_cvt_pk_bf16_f32 v39, v76, v77
	v_cvt_pk_bf16_f32 v38, v78, v79
	global_store_dwordx2 v[0:1], v[38:39], off offset:512
	v_pk_mul_f32 v[38:39], v[78:79], v[78:79]
	v_pk_mul_f32 v[42:43], v[76:77], v[76:77]
	s_nop 0
	v_pk_mov_b32 v[60:61], v[38:39], v[42:43] op_sel:[1,0]
	v_mov_b32_e32 v39, v43
	v_mov_b32_e32 v42, v84
	v_mov_b32_e32 v43, v86
	v_mov_b32_e32 v86, v85
	v_pk_add_f32 v[38:39], v[60:61], v[38:39]
	v_pk_mul_f32 v[42:43], v[120:121], v[42:43] op_sel_hi:[0,1]
	v_pk_mul_f32 v[60:61], v[120:121], v[86:87] op_sel_hi:[0,1]
	v_pk_fma_f32 v[80:81], v[60:61], v[50:51], v[58:59]
	v_pk_fma_f32 v[82:83], v[42:43], v[48:49], v[56:57]
	v_cvt_pk_bf16_f32 v43, v80, v81
	v_cvt_pk_bf16_f32 v42, v82, v83
	global_store_dwordx2 v[40:41], v[42:43], off offset:512
	v_pk_mul_f32 v[42:43], v[82:83], v[82:83]
	v_pk_mul_f32 v[56:57], v[80:81], v[80:81]
	s_nop 0
	v_pk_mov_b32 v[58:59], v[42:43], v[56:57] op_sel:[1,0]
	v_mov_b32_e32 v43, v57
	v_mov_b32_e32 v56, v162
	v_mov_b32_e32 v57, v164
	v_mov_b32_e32 v164, v163
	v_pk_add_f32 v[42:43], v[58:59], v[42:43]
	v_pk_mul_f32 v[56:57], v[146:147], v[56:57] op_sel_hi:[0,1]
	v_pk_mul_f32 v[58:59], v[146:147], v[164:165] op_sel_hi:[0,1]
	v_pk_fma_f32 v[84:85], v[58:59], v[50:51], v[68:69]
	v_pk_fma_f32 v[86:87], v[56:57], v[48:49], v[66:67]
	v_cvt_pk_bf16_f32 v57, v84, v85
	v_cvt_pk_bf16_f32 v56, v86, v87
	global_store_dwordx2 v[88:89], v[56:57], off offset:512
	v_pk_mul_f32 v[56:57], v[86:87], v[86:87]
	v_pk_mul_f32 v[58:59], v[84:85], v[84:85]
	s_nop 0
	v_pk_mov_b32 v[60:61], v[56:57], v[58:59] op_sel:[1,0]
	v_mov_b32_e32 v57, v59
	v_pk_add_f32 v[162:163], v[60:61], v[56:57]
	v_mov_b32_e32 v56, v166
	v_mov_b32_e32 v57, v172
	v_mov_b32_e32 v172, v167
	v_pk_mul_f32 v[56:57], v[130:131], v[56:57] op_sel_hi:[0,1]
	v_pk_mul_f32 v[58:59], v[130:131], v[172:173] op_sel_hi:[0,1]
	v_pk_fma_f32 v[72:73], v[50:51], v[58:59], v[124:125]
	v_pk_fma_f32 v[74:75], v[48:49], v[56:57], v[122:123]
	v_cvt_pk_bf16_f32 v49, v72, v73
	v_cvt_pk_bf16_f32 v48, v74, v75
	global_store_dwordx2 v[106:107], v[48:49], off offset:512
	v_pk_mul_f32 v[48:49], v[74:75], v[74:75]
	v_pk_mul_f32 v[50:51], v[72:73], v[72:73]
	s_nop 0
	v_pk_mov_b32 v[56:57], v[48:49], v[50:51] op_sel:[1,0]
	v_mov_b32_e32 v49, v51
	v_pk_add_f32 v[122:123], v[56:57], v[48:49]
	global_load_dwordx4 v[48:51], v192, s[0:1]
	global_load_dwordx4 v[56:59], v[14:15], off
	s_waitcnt vmcnt(0)
	v_pk_mul_f32 v[50:51], v[50:51], v[58:59]
	v_pk_mul_f32 v[48:49], v[48:49], v[56:57]
	v_pk_mul_f32 v[56:57], v[128:129], v[132:133] op_sel_hi:[0,1]
	v_pk_mul_f32 v[58:59], v[128:129], v[134:135] op_sel_hi:[0,1]
	v_pk_fma_f32 v[60:61], v[58:59], v[50:51], v[36:37]
	v_pk_fma_f32 v[66:67], v[56:57], v[48:49], v[34:35]
	v_cvt_pk_bf16_f32 v35, v60, v61
	v_cvt_pk_bf16_f32 v34, v66, v67
	global_store_dwordx2 v[0:1], v[34:35], off offset:1024
	v_pk_mul_f32 v[34:35], v[120:121], v[136:137] op_sel_hi:[0,1]
	v_pk_mul_f32 v[36:37], v[120:121], v[138:139] op_sel_hi:[0,1]
	v_pk_fma_f32 v[62:63], v[36:37], v[50:51], v[54:55]
	v_pk_fma_f32 v[68:69], v[34:35], v[48:49], v[52:53]
	v_cvt_pk_bf16_f32 v35, v62, v63
	v_cvt_pk_bf16_f32 v34, v68, v69
	global_store_dwordx2 v[40:41], v[34:35], off offset:1024
	v_pk_mul_f32 v[34:35], v[146:147], v[154:155] op_sel_hi:[0,1]
	v_pk_mul_f32 v[36:37], v[146:147], v[156:157] op_sel_hi:[0,1]
	v_pk_fma_f32 v[64:65], v[36:37], v[50:51], v[64:65]
	v_pk_fma_f32 v[70:71], v[34:35], v[48:49], v[70:71]
	v_cvt_pk_bf16_f32 v35, v64, v65
	v_cvt_pk_bf16_f32 v34, v70, v71
	global_store_dwordx2 v[88:89], v[34:35], off offset:1024
	v_pk_mul_f32 v[34:35], v[130:131], v[158:159] op_sel_hi:[0,1]
	v_pk_mul_f32 v[36:37], v[130:131], v[160:161] op_sel_hi:[0,1]
	v_pk_fma_f32 v[56:57], v[36:37], v[50:51], v[114:115]
	v_pk_fma_f32 v[58:59], v[34:35], v[48:49], v[112:113]
	v_cvt_pk_bf16_f32 v35, v56, v57
	v_cvt_pk_bf16_f32 v34, v58, v59
	global_store_dwordx2 v[106:107], v[34:35], off offset:1024
	global_load_dwordx4 v[34:37], v193, s[0:1]
	s_nop 0
	global_load_dwordx4 v[48:51], v[16:17], off
	s_waitcnt vmcnt(0)
	v_pk_mul_f32 v[50:51], v[36:37], v[50:51]
	v_pk_mul_f32 v[48:49], v[34:35], v[48:49]
	v_pk_mul_f32 v[34:35], v[128:129], v[118:119] op_sel_hi:[0,1]
	v_pk_mul_f32 v[36:37], v[128:129], v[116:117] op_sel_hi:[0,1]
	v_pk_fma_f32 v[32:33], v[36:37], v[50:51], v[32:33]
	v_pk_fma_f32 v[34:35], v[34:35], v[48:49], v[2:3]
	v_cvt_pk_bf16_f32 v3, v32, v33
	v_cvt_pk_bf16_f32 v2, v34, v35
	global_store_dwordx2 v[0:1], v[2:3], off offset:1536
	v_mul_f32_e32 v2, v34, v34
	v_pk_add_f32 v[0:1], v[198:199], v[198:199] op_sel:[0,1] op_sel_hi:[1,0]
	v_mul_f32_e32 v36, v35, v35
	v_mov_b32_e32 v1, v2
	v_pk_add_f32 v[2:3], v[38:39], v[38:39] op_sel:[0,1] op_sel_hi:[1,0]
	v_mul_f32_e32 v37, v32, v32
	v_mov_b32_e32 v3, v36
	v_pk_add_f32 v[0:1], v[0:1], v[2:3]
	v_mul_f32_e32 v2, v67, v67
	v_pk_fma_f32 v[2:3], v[66:67], v[66:67], v[2:3] op_sel_hi:[1,1,0]
	v_mul_f32_e32 v36, v61, v61
	v_mul_f32_e32 v52, v33, v33
	v_mov_b32_e32 v3, v37
	v_pk_fma_f32 v[36:37], v[60:61], v[60:61], v[36:37] op_sel_hi:[1,1,0]
	v_mov_b32_e32 v128, v131
	v_mov_b32_e32 v37, v52
	v_pk_add_f32 v[2:3], v[2:3], v[36:37]
	v_pk_mul_f32 v[36:37], v[120:121], v[126:127] op_sel_hi:[0,1]
	v_pk_add_f32 v[0:1], v[0:1], v[2:3]
	v_pk_mul_f32 v[2:3], v[120:121], v[128:129] op_sel_hi:[0,1]
	v_pk_fma_f32 v[36:37], v[36:37], v[50:51], v[46:47]
	v_pk_fma_f32 v[38:39], v[2:3], v[48:49], v[44:45]
	v_cvt_pk_bf16_f32 v3, v36, v37
	v_cvt_pk_bf16_f32 v2, v38, v39
	global_store_dwordx2 v[40:41], v[2:3], off offset:1536
	v_mul_f32_e32 v40, v38, v38
	v_pk_add_f32 v[2:3], v[200:201], v[200:201] op_sel:[0,1] op_sel_hi:[1,0]
	v_mul_f32_e32 v44, v39, v39
	v_mov_b32_e32 v3, v40
	v_pk_add_f32 v[40:41], v[42:43], v[42:43] op_sel:[0,1] op_sel_hi:[1,0]
	v_mul_f32_e32 v42, v63, v63
	v_mov_b32_e32 v41, v44
	v_pk_add_f32 v[2:3], v[2:3], v[40:41]
	v_mul_f32_e32 v40, v69, v69
	v_mul_f32_e32 v45, v36, v36
	v_mul_f32_e32 v46, v37, v37
	v_pk_fma_f32 v[40:41], v[68:69], v[68:69], v[40:41] op_sel_hi:[1,1,0]
	v_pk_fma_f32 v[42:43], v[62:63], v[62:63], v[42:43] op_sel_hi:[1,1,0]
	v_mov_b32_e32 v41, v45
	v_mov_b32_e32 v43, v46
	v_pk_add_f32 v[40:41], v[40:41], v[42:43]
	v_pk_mul_f32 v[42:43], v[146:147], v[144:145] op_sel_hi:[0,1]
	v_pk_add_f32 v[2:3], v[2:3], v[40:41]
	v_pk_mul_f32 v[40:41], v[146:147], v[142:143] op_sel_hi:[0,1]
	v_pk_fma_f32 v[40:41], v[40:41], v[50:51], v[104:105]
	v_pk_fma_f32 v[42:43], v[42:43], v[48:49], v[102:103]
	v_cvt_pk_bf16_f32 v45, v40, v41
	v_cvt_pk_bf16_f32 v44, v42, v43
	global_store_dwordx2 v[88:89], v[44:45], off offset:1536
	v_mul_f32_e32 v46, v42, v42
	v_pk_add_f32 v[44:45], v[176:177], v[176:177] op_sel:[0,1] op_sel_hi:[1,0]
	v_mul_f32_e32 v52, v43, v43
	v_mov_b32_e32 v45, v46
	v_pk_add_f32 v[46:47], v[162:163], v[162:163] op_sel:[0,1] op_sel_hi:[1,0]
	v_mul_f32_e32 v53, v40, v40
	v_mov_b32_e32 v47, v52
	v_pk_add_f32 v[44:45], v[44:45], v[46:47]
	v_mul_f32_e32 v46, v71, v71
	v_pk_fma_f32 v[46:47], v[70:71], v[70:71], v[46:47] op_sel_hi:[1,1,0]
	v_mul_f32_e32 v52, v65, v65
	v_mul_f32_e32 v54, v41, v41
	v_mov_b32_e32 v47, v53
	v_pk_fma_f32 v[52:53], v[64:65], v[64:65], v[52:53] op_sel_hi:[1,1,0]
	s_nop 0
	v_mov_b32_e32 v53, v54
	v_pk_add_f32 v[46:47], v[46:47], v[52:53]
	s_nop 0
	v_pk_add_f32 v[52:53], v[44:45], v[46:47]
	v_pk_mul_f32 v[46:47], v[130:131], v[150:151] op_sel_hi:[0,1]
	v_pk_mul_f32 v[44:45], v[130:131], v[148:149] op_sel_hi:[0,1]
	v_pk_fma_f32 v[44:45], v[44:45], v[50:51], v[110:111]
	v_pk_fma_f32 v[46:47], v[46:47], v[48:49], v[108:109]
	v_cvt_pk_bf16_f32 v49, v44, v45
	v_cvt_pk_bf16_f32 v48, v46, v47
	global_store_dwordx2 v[106:107], v[48:49], off offset:1536
	v_mul_f32_e32 v50, v46, v46
	v_pk_add_f32 v[48:49], v[178:179], v[178:179] op_sel:[0,1] op_sel_hi:[1,0]
	v_mul_f32_e32 v54, v47, v47
	v_mov_b32_e32 v49, v50
	v_pk_add_f32 v[50:51], v[122:123], v[122:123] op_sel:[0,1] op_sel_hi:[1,0]
	v_mul_f32_e32 v55, v44, v44
	v_mov_b32_e32 v51, v54
	v_pk_add_f32 v[48:49], v[48:49], v[50:51]
	v_mul_f32_e32 v50, v59, v59
	v_pk_fma_f32 v[50:51], v[58:59], v[58:59], v[50:51] op_sel_hi:[1,1,0]
	v_mul_f32_e32 v54, v57, v57
	v_mul_f32_e32 v88, v45, v45
	v_mov_b32_e32 v51, v55
	v_pk_fma_f32 v[54:55], v[56:57], v[56:57], v[54:55] op_sel_hi:[1,1,0]
	s_nop 0
	v_mov_b32_e32 v55, v88
	v_pk_add_f32 v[50:51], v[50:51], v[54:55]
	s_nop 0
	v_pk_add_f32 v[54:55], v[48:49], v[50:51]
	v_mov_b32_e32 v48, v2
	v_mov_b32_e32 v49, v0
	v_mov_b32_e32 v0, v3
	v_pk_add_f32 v[0:1], v[48:49], v[0:1]
	ds_bpermute_b32 v3, v184, v1
	ds_bpermute_b32 v2, v184, v0
	s_waitcnt lgkmcnt(0)
	v_pk_add_f32 v[0:1], v[0:1], v[2:3]
	ds_bpermute_b32 v3, v185, v1
	ds_bpermute_b32 v2, v185, v0
	s_waitcnt lgkmcnt(0)
	v_pk_add_f32 v[0:1], v[0:1], v[2:3]
	ds_bpermute_b32 v3, v186, v1
	ds_bpermute_b32 v2, v186, v0
	s_waitcnt lgkmcnt(0)
	v_pk_add_f32 v[0:1], v[0:1], v[2:3]
	ds_bpermute_b32 v3, v187, v1
	ds_bpermute_b32 v2, v187, v0
	s_waitcnt lgkmcnt(0)
	v_pk_add_f32 v[0:1], v[0:1], v[2:3]
	ds_bpermute_b32 v3, v188, v1
	ds_bpermute_b32 v2, v188, v0
	s_waitcnt lgkmcnt(0)
	v_pk_add_f32 v[0:1], v[0:1], v[2:3]
	ds_bpermute_b32 v3, v189, v1
	ds_bpermute_b32 v2, v189, v0
	s_waitcnt lgkmcnt(0)
	v_pk_add_f32 v[0:1], v[0:1], v[2:3]
	s_nop 0
	v_pk_fma_f32 v[0:1], v[0:1], s[6:7], v[140:141] op_sel_hi:[1,0,0]
	s_nop 0
	v_mul_f32_e32 v2, 0x4b800000, v1
	v_cmp_gt_f32_e64 s[0:1], s21, v1
	v_cmp_gt_f32_e32 vcc, s21, v0
	s_nop 0
	v_cndmask_b32_e64 v1, v1, v2, s[0:1]
	v_rsq_f32_e32 v1, v1
	s_nop 0
	v_mul_f32_e32 v2, 0x45800000, v1
	v_cndmask_b32_e64 v50, v1, v2, s[0:1]
	v_mul_f32_e32 v1, 0x4b800000, v0
	v_cndmask_b32_e32 v0, v0, v1, vcc
	v_rsq_f32_e32 v0, v0
	v_pk_mul_f32 v[78:79], v[78:79], v[50:51] op_sel_hi:[1,0]
	v_pk_mul_f32 v[76:77], v[76:77], v[50:51] op_sel_hi:[1,0]
	v_pk_mul_f32 v[66:67], v[66:67], v[50:51] op_sel_hi:[1,0]
	v_mul_f32_e32 v1, 0x45800000, v0
	v_cndmask_b32_e32 v48, v0, v1, vcc
	v_mov_b32_e32 v0, v54
	v_mov_b32_e32 v1, v52
	v_mov_b32_e32 v52, v55
	v_pk_add_f32 v[0:1], v[0:1], v[52:53]
	ds_bpermute_b32 v3, v184, v1
	ds_bpermute_b32 v2, v184, v0
	v_pk_mul_f32 v[96:97], v[96:97], v[48:49] op_sel_hi:[1,0]
	v_pk_mul_f32 v[94:95], v[94:95], v[48:49] op_sel_hi:[1,0]
	v_pk_mul_f32 v[60:61], v[60:61], v[50:51] op_sel_hi:[1,0]
	v_pk_mul_f32 v[62:63], v[62:63], v[48:49] op_sel_hi:[1,0]
	s_waitcnt lgkmcnt(0)
	v_pk_add_f32 v[0:1], v[0:1], v[2:3]
	ds_bpermute_b32 v3, v185, v1
	ds_bpermute_b32 v2, v185, v0
	v_pk_mul_f32 v[34:35], v[34:35], v[50:51] op_sel_hi:[1,0]
	v_pk_mul_f32 v[32:33], v[32:33], v[50:51] op_sel_hi:[1,0]
	s_waitcnt lgkmcnt(0)
	v_pk_add_f32 v[0:1], v[0:1], v[2:3]
	ds_bpermute_b32 v3, v186, v1
	ds_bpermute_b32 v2, v186, v0
	s_waitcnt lgkmcnt(0)
	v_pk_add_f32 v[0:1], v[0:1], v[2:3]
	ds_bpermute_b32 v3, v187, v1
	ds_bpermute_b32 v2, v187, v0
	s_waitcnt lgkmcnt(0)
	v_pk_add_f32 v[0:1], v[0:1], v[2:3]
	ds_bpermute_b32 v3, v188, v1
	ds_bpermute_b32 v2, v188, v0
	s_waitcnt lgkmcnt(0)
	v_pk_add_f32 v[0:1], v[0:1], v[2:3]
	ds_bpermute_b32 v3, v189, v1
	ds_bpermute_b32 v2, v189, v0
	s_waitcnt lgkmcnt(0)
	v_pk_add_f32 v[0:1], v[0:1], v[2:3]
	s_nop 0
	v_pk_fma_f32 v[0:1], v[0:1], s[6:7], v[140:141] op_sel_hi:[1,0,0]
	s_nop 0
	v_mul_f32_e32 v2, 0x4b800000, v1
	v_cmp_gt_f32_e64 s[0:1], s21, v1
	v_cmp_gt_f32_e32 vcc, s21, v0
	s_nop 0
	v_cndmask_b32_e64 v1, v1, v2, s[0:1]
	v_rsq_f32_e32 v1, v1
	s_nop 0
	v_mul_f32_e32 v2, 0x45800000, v1
	v_cndmask_b32_e64 v54, v1, v2, s[0:1]
	v_mul_f32_e32 v1, 0x4b800000, v0
	v_cndmask_b32_e32 v0, v0, v1, vcc
	v_rsq_f32_e32 v0, v0
	s_add_u32 s0, s5, 0x6000
	s_addc_u32 s1, s13, 0
	s_add_u32 s12, s5, 0x7000
	v_mul_f32_e32 v1, 0x45800000, v0
	v_cndmask_b32_e32 v52, v0, v1, vcc
	s_addc_u32 s13, s13, 0
	global_load_dwordx4 v[104:107], v[18:19], off
	global_load_dwordx4 v[108:111], v190, s[12:13]
	global_load_dwordx4 v[0:3], v190, s[0:1]
	v_pk_mul_f32 v[92:93], v[92:93], v[52:53] op_sel_hi:[1,0]
	v_pk_mul_f32 v[90:91], v[90:91], v[52:53] op_sel_hi:[1,0]
	s_or_b32 s16, s10, 0x1000
	v_pk_mul_f32 v[74:75], v[74:75], v[52:53] op_sel_hi:[1,0]
	v_pk_mul_f32 v[72:73], v[72:73], v[52:53] op_sel_hi:[1,0]
	v_pk_mul_f32 v[58:59], v[58:59], v[52:53] op_sel_hi:[1,0]
	v_pk_mul_f32 v[56:57], v[56:57], v[52:53] op_sel_hi:[1,0]
	s_add_i32 s2, s2, s3
	s_add_i32 s7, s7, s9
	s_add_i32 s18, s18, s19
	s_add_i32 s4, s4, s20
	s_waitcnt vmcnt(1)
	v_pk_add_f32 v[88:89], v[110:111], 1.0 op_sel_hi:[1,0]
	v_pk_add_f32 v[108:109], v[108:109], 1.0 op_sel_hi:[1,0]
	v_pk_mul_f32 v[102:103], v[106:107], v[88:89]
	v_pk_mul_f32 v[104:105], v[104:105], v[108:109]
	v_pk_mul_f32 v[88:89], v[182:183], v[50:51] op_sel_hi:[1,0]
	v_pk_mul_f32 v[106:107], v[174:175], v[50:51] op_sel_hi:[1,0]
	s_waitcnt vmcnt(0)
	v_pk_fma_f32 v[88:89], v[88:89], v[104:105], v[0:1]
	v_pk_fma_f32 v[94:95], v[94:95], v[102:103], v[2:3]
	v_pk_fma_f32 v[96:97], v[96:97], v[104:105], v[0:1]
	v_pk_fma_f32 v[108:109], v[106:107], v[102:103], v[2:3]
	v_cvt_pk_bf16_f32 v106, v88, v89
	v_lshl_add_u64 v[88:89], v[8:9], 0, s[10:11]
	v_cvt_pk_bf16_f32 v96, v96, v97
	v_cvt_pk_bf16_f32 v97, v94, v95
	global_store_dwordx2 v[88:89], v[96:97], off offset:2048
	v_pk_mul_f32 v[94:95], v[100:101], v[54:55] op_sel_hi:[1,0]
	v_pk_mul_f32 v[96:97], v[98:99], v[54:55] op_sel_hi:[1,0]
	v_pk_fma_f32 v[94:95], v[104:105], v[94:95], v[0:1]
	v_pk_fma_f32 v[96:97], v[102:103], v[96:97], v[2:3]
	v_pk_fma_f32 v[2:3], v[102:103], v[90:91], v[2:3]
	v_pk_fma_f32 v[0:1], v[104:105], v[92:93], v[0:1]
	s_or_b32 s10, s10, 0x1800
	v_cvt_pk_bf16_f32 v107, v108, v109
	v_cvt_pk_bf16_f32 v94, v94, v95
	v_cvt_pk_bf16_f32 v95, v96, v97
	v_lshl_add_u64 v[96:97], v[8:9], 0, s[16:17]
	v_cvt_pk_bf16_f32 v0, v0, v1
	v_cvt_pk_bf16_f32 v1, v2, v3
	v_lshl_add_u64 v[2:3], v[8:9], 0, s[10:11]
	global_store_dwordx2 v[88:89], v[106:107], off
	global_store_dwordx2 v[96:97], v[94:95], off
	global_store_dwordx2 v[2:3], v[0:1], off
	global_load_dwordx4 v[0:3], v[20:21], off
	s_nop 0
	global_load_dwordx4 v[90:93], v191, s[12:13]
	global_load_dwordx4 v[94:97], v191, s[0:1]
	s_cmpk_lt_i32 s2, 0x4000
	s_waitcnt vmcnt(1)
	v_pk_add_f32 v[92:93], v[92:93], 1.0 op_sel_hi:[1,0]
	v_pk_add_f32 v[90:91], v[90:91], 1.0 op_sel_hi:[1,0]
	v_pk_mul_f32 v[2:3], v[2:3], v[92:93]
	v_pk_mul_f32 v[0:1], v[0:1], v[90:91]
	s_waitcnt vmcnt(0)
	v_pk_fma_f32 v[76:77], v[76:77], v[2:3], v[96:97]
	v_pk_fma_f32 v[78:79], v[78:79], v[0:1], v[94:95]
	s_nop 0
	v_cvt_pk_bf16_f32 v78, v78, v79
	v_cvt_pk_bf16_f32 v79, v76, v77
	global_store_dwordx2 v[88:89], v[78:79], off offset:512
	v_pk_mul_f32 v[76:77], v[82:83], v[48:49] op_sel_hi:[1,0]
	v_pk_mul_f32 v[78:79], v[80:81], v[48:49] op_sel_hi:[1,0]
	v_pk_fma_f32 v[76:77], v[76:77], v[0:1], v[94:95]
	v_pk_fma_f32 v[78:79], v[78:79], v[2:3], v[96:97]
	v_cvt_pk_bf16_f32 v76, v76, v77
	v_cvt_pk_bf16_f32 v77, v78, v79
	global_store_dwordx2 v[88:89], v[76:77], off offset:2560
	v_pk_mul_f32 v[76:77], v[86:87], v[54:55] op_sel_hi:[1,0]
	v_pk_mul_f32 v[78:79], v[84:85], v[54:55] op_sel_hi:[1,0]
	v_pk_fma_f32 v[76:77], v[76:77], v[0:1], v[94:95]
	v_pk_fma_f32 v[78:79], v[78:79], v[2:3], v[96:97]
	v_pk_fma_f32 v[2:3], v[2:3], v[72:73], v[96:97]
	v_pk_fma_f32 v[0:1], v[0:1], v[74:75], v[94:95]
	v_cvt_pk_bf16_f32 v76, v76, v77
	v_cvt_pk_bf16_f32 v77, v78, v79
	v_lshl_add_u64 v[78:79], v[22:23], 0, s[16:17]
	v_cvt_pk_bf16_f32 v0, v0, v1
	v_cvt_pk_bf16_f32 v1, v2, v3
	v_lshl_add_u64 v[2:3], v[22:23], 0, s[10:11]
	global_store_dwordx2 v[78:79], v[76:77], off
	global_store_dwordx2 v[2:3], v[0:1], off
	global_load_dwordx4 v[0:3], v[24:25], off
	s_nop 0
	global_load_dwordx4 v[72:75], v192, s[12:13]
	global_load_dwordx4 v[76:79], v192, s[0:1]
	s_waitcnt vmcnt(1)
	v_pk_add_f32 v[74:75], v[74:75], 1.0 op_sel_hi:[1,0]
	v_pk_add_f32 v[72:73], v[72:73], 1.0 op_sel_hi:[1,0]
	v_pk_mul_f32 v[2:3], v[2:3], v[74:75]
	v_pk_mul_f32 v[0:1], v[0:1], v[72:73]
	s_waitcnt vmcnt(0)
	v_pk_fma_f32 v[60:61], v[60:61], v[2:3], v[78:79]
	v_pk_fma_f32 v[66:67], v[66:67], v[0:1], v[76:77]
	v_pk_fma_f32 v[62:63], v[62:63], v[2:3], v[78:79]
	v_cvt_pk_bf16_f32 v66, v66, v67
	v_cvt_pk_bf16_f32 v67, v60, v61
	v_pk_mul_f32 v[60:61], v[68:69], v[48:49] op_sel_hi:[1,0]
	global_store_dwordx2 v[88:89], v[66:67], off offset:1024
	v_pk_fma_f32 v[60:61], v[60:61], v[0:1], v[76:77]
	s_nop 0
	v_cvt_pk_bf16_f32 v60, v60, v61
	v_cvt_pk_bf16_f32 v61, v62, v63
	global_store_dwordx2 v[88:89], v[60:61], off offset:3072
	v_pk_mul_f32 v[60:61], v[70:71], v[54:55] op_sel_hi:[1,0]
	v_pk_mul_f32 v[62:63], v[64:65], v[54:55] op_sel_hi:[1,0]
	v_pk_fma_f32 v[60:61], v[60:61], v[0:1], v[76:77]
	v_pk_fma_f32 v[62:63], v[62:63], v[2:3], v[78:79]
	v_pk_fma_f32 v[2:3], v[56:57], v[2:3], v[78:79]
	v_pk_fma_f32 v[0:1], v[58:59], v[0:1], v[76:77]
	v_cvt_pk_bf16_f32 v60, v60, v61
	v_cvt_pk_bf16_f32 v61, v62, v63
	v_lshl_add_u64 v[62:63], v[26:27], 0, s[16:17]
	v_cvt_pk_bf16_f32 v0, v0, v1
	v_cvt_pk_bf16_f32 v1, v2, v3
	v_lshl_add_u64 v[2:3], v[26:27], 0, s[10:11]
	global_store_dwordx2 v[62:63], v[60:61], off
	global_store_dwordx2 v[2:3], v[0:1], off
	global_load_dwordx4 v[0:3], v[28:29], off
	s_nop 0
	global_load_dwordx4 v[56:59], v193, s[12:13]
	global_load_dwordx4 v[60:63], v193, s[0:1]
	s_waitcnt vmcnt(1)
	v_pk_add_f32 v[58:59], v[58:59], 1.0 op_sel_hi:[1,0]
	v_pk_add_f32 v[56:57], v[56:57], 1.0 op_sel_hi:[1,0]
	v_pk_mul_f32 v[2:3], v[2:3], v[58:59]
	v_pk_mul_f32 v[0:1], v[0:1], v[56:57]
	s_waitcnt vmcnt(0)
	v_pk_fma_f32 v[32:33], v[32:33], v[2:3], v[62:63]
	v_pk_fma_f32 v[34:35], v[34:35], v[0:1], v[60:61]
	s_nop 0
	v_cvt_pk_bf16_f32 v34, v34, v35
	v_cvt_pk_bf16_f32 v35, v32, v33
	global_store_dwordx2 v[88:89], v[34:35], off offset:1536
	v_pk_mul_f32 v[32:33], v[38:39], v[48:49] op_sel_hi:[1,0]
	v_pk_mul_f32 v[34:35], v[36:37], v[48:49] op_sel_hi:[1,0]
	v_pk_fma_f32 v[32:33], v[32:33], v[0:1], v[60:61]
	v_pk_fma_f32 v[34:35], v[34:35], v[2:3], v[62:63]
	v_cvt_pk_bf16_f32 v32, v32, v33
	v_cvt_pk_bf16_f32 v33, v34, v35
	global_store_dwordx2 v[88:89], v[32:33], off offset:3584
	v_pk_mul_f32 v[32:33], v[42:43], v[54:55] op_sel_hi:[1,0]
	v_pk_mul_f32 v[34:35], v[40:41], v[54:55] op_sel_hi:[1,0]
	v_pk_fma_f32 v[32:33], v[32:33], v[0:1], v[60:61]
	v_pk_fma_f32 v[34:35], v[34:35], v[2:3], v[62:63]
	v_cvt_pk_bf16_f32 v32, v32, v33
	v_cvt_pk_bf16_f32 v33, v34, v35
	v_lshl_add_u64 v[34:35], v[30:31], 0, s[16:17]
	global_store_dwordx2 v[34:35], v[32:33], off
	v_pk_mul_f32 v[32:33], v[46:47], v[52:53] op_sel_hi:[1,0]
	v_pk_mul_f32 v[34:35], v[44:45], v[52:53] op_sel_hi:[1,0]
	v_pk_fma_f32 v[0:1], v[32:33], v[0:1], v[60:61]
	v_pk_fma_f32 v[2:3], v[34:35], v[2:3], v[62:63]
	v_cvt_pk_bf16_f32 v0, v0, v1
	v_cvt_pk_bf16_f32 v1, v2, v3
	v_lshl_add_u64 v[2:3], v[30:31], 0, s[10:11]
	global_store_dwordx2 v[2:3], v[0:1], off
	s_cbranch_scc1 .LBB0_912
